# v014 + attention queue hands out one (b,h) at a time per XCD; removed stray lgkmcnt(0) at two K-loop heads
# baseline (speedup 1.0000x reference)
.LBB0_1942:
	ds_read_b128 v[130:133], v200
	ds_read_b128 v[134:137], v200 offset:1024
	ds_read_b128 v[138:141], v200 offset:2048
	ds_read_b128 v[142:145], v200 offset:3072
	ds_read_b128 v[146:149], v201
	ds_read_b128 v[150:153], v201 offset:1024
	ds_read_b128 v[154:157], v201 offset:2048
	ds_read_b128 v[158:161], v201 offset:3072
	s_add_u32 s26, s8, 0xfff80080
	s_addc_u32 s27, s9, -1
	s_cmp_eq_u32 s53, 28
	s_cselect_b32 s29, s7, s27
	s_cselect_b32 s28, s21, s26
	s_cselect_b32 s27, s19, s52
	s_cselect_b32 s26, s50, s51
	v_lshl_add_u64 v[216:217], s[8:9], 0, v[190:191]
	s_add_i32 m0, s35, 0xc000
	ds_read_b128 v[162:165], v202
	ds_read_b128 v[166:169], v202 offset:1024
	ds_read_b128 v[170:173], v202 offset:2048
	ds_read_b128 v[174:177], v202 offset:3072
	ds_read_b128 v[178:181], v202 offset:4096
	ds_read_b128 v[204:207], v202 offset:5120
	ds_read_b128 v[208:211], v202 offset:6144
	ds_read_b128 v[212:215], v202 offset:7168
	global_load_lds_dwordx4 v[216:217], off
	v_lshl_add_u64 v[216:217], s[8:9], 0, v[192:193]
	s_add_i32 m0, s35, 0xe000
	s_nop 0
	global_load_lds_dwordx4 v[216:217], off
	s_waitcnt vmcnt(8)
	s_waitcnt lgkmcnt(0)
	s_barrier
	s_setprio 1
	s_waitcnt lgkmcnt(0)
	v_mfma_f32_16x16x32_bf16 v[126:129], v[130:133], v[162:165], v[126:129]
	v_mfma_f32_16x16x32_bf16 v[122:125], v[138:141], v[162:165], v[122:125]
	v_mfma_f32_16x16x32_bf16 v[118:121], v[130:133], v[170:173], v[118:121]
	v_mfma_f32_16x16x32_bf16 v[110:113], v[138:141], v[170:173], v[110:113]
	v_mfma_f32_16x16x32_bf16 v[102:105], v[130:133], v[178:181], v[102:105]
	v_mfma_f32_16x16x32_bf16 v[94:97], v[138:141], v[178:181], v[94:97]
	v_mfma_f32_16x16x32_bf16 v[86:89], v[130:133], v[208:211], v[86:89]
	v_mfma_f32_16x16x32_bf16 v[78:81], v[138:141], v[208:211], v[78:81]
	v_mfma_f32_16x16x32_bf16 v[126:129], v[134:137], v[166:169], v[126:129]
	v_mfma_f32_16x16x32_bf16 v[122:125], v[142:145], v[166:169], v[122:125]
	v_mfma_f32_16x16x32_bf16 v[118:121], v[134:137], v[174:177], v[118:121]
	v_mfma_f32_16x16x32_bf16 v[110:113], v[142:145], v[174:177], v[110:113]
	v_mfma_f32_16x16x32_bf16 v[102:105], v[134:137], v[204:207], v[102:105]
	v_mfma_f32_16x16x32_bf16 v[94:97], v[142:145], v[204:207], v[94:97]
	v_mfma_f32_16x16x32_bf16 v[86:89], v[134:137], v[212:215], v[86:89]
	v_mfma_f32_16x16x32_bf16 v[78:81], v[142:145], v[212:215], v[78:81]
	s_setprio 0
	s_setprio 1
	v_mfma_f32_16x16x32_bf16 v[114:117], v[146:149], v[162:165], v[114:117]
	v_mfma_f32_16x16x32_bf16 v[106:109], v[154:157], v[162:165], v[106:109]
	v_mfma_f32_16x16x32_bf16 v[98:101], v[146:149], v[170:173], v[98:101]
	v_mfma_f32_16x16x32_bf16 v[90:93], v[154:157], v[170:173], v[90:93]
	v_mfma_f32_16x16x32_bf16 v[82:85], v[146:149], v[178:181], v[82:85]
	v_mfma_f32_16x16x32_bf16 v[74:77], v[154:157], v[178:181], v[74:77]
	v_mfma_f32_16x16x32_bf16 v[70:73], v[146:149], v[208:211], v[70:73]
	v_mfma_f32_16x16x32_bf16 v[66:69], v[154:157], v[208:211], v[66:69]
	v_mfma_f32_16x16x32_bf16 v[114:117], v[150:153], v[166:169], v[114:117]
	v_mfma_f32_16x16x32_bf16 v[106:109], v[158:161], v[166:169], v[106:109]
	v_mfma_f32_16x16x32_bf16 v[98:101], v[150:153], v[174:177], v[98:101]
	v_mfma_f32_16x16x32_bf16 v[90:93], v[158:161], v[174:177], v[90:93]
	v_mfma_f32_16x16x32_bf16 v[82:85], v[150:153], v[204:207], v[82:85]
	v_mfma_f32_16x16x32_bf16 v[74:77], v[158:161], v[204:207], v[74:77]
	v_mfma_f32_16x16x32_bf16 v[70:73], v[150:153], v[212:215], v[70:73]
	v_mfma_f32_16x16x32_bf16 v[66:69], v[158:161], v[212:215], v[66:69]
	s_setprio 0
	s_barrier
	s_add_i32 s54, s45, s31
	v_lshl_add_u64 v[216:217], s[26:27], 0, v[186:187]
	s_mov_b32 m0, s54
	ds_read_b128 v[162:165], v202 offset:16384
	ds_read_b128 v[166:169], v202 offset:17408
	ds_read_b128 v[170:173], v202 offset:18432
	ds_read_b128 v[174:177], v202 offset:19456
	ds_read_b128 v[178:181], v202 offset:20480
	ds_read_b128 v[204:207], v202 offset:21504
	ds_read_b128 v[208:211], v202 offset:22528
	ds_read_b128 v[212:215], v202 offset:23552
	global_load_lds_dwordx4 v[216:217], off
	s_add_i32 m0, s54, 0x2000
	s_add_u32 s54, s26, 0x80000
	v_lshl_add_u64 v[218:219], s[26:27], 0, v[182:183]
	s_addc_u32 s55, s27, 0
	s_add_i32 s56, s46, s31
	global_load_lds_dwordx4 v[218:219], off
	v_lshl_add_u64 v[220:221], s[54:55], 0, v[186:187]
	s_mov_b32 m0, s56
	v_lshl_add_u64 v[222:223], s[28:29], 0, v[184:185]
	global_load_lds_dwordx4 v[220:221], off
	v_lshl_add_u64 v[220:221], s[54:55], 0, v[182:183]
	s_add_i32 m0, s56, 0x2000
	s_nop 0
	global_load_lds_dwordx4 v[220:221], off
	v_lshl_add_u64 v[220:221], s[28:29], 0, v[188:189]
	s_mov_b32 m0, s35
	s_nop 0
	global_load_lds_dwordx4 v[220:221], off
	s_mov_b32 m0, s36
	s_nop 0
	global_load_lds_dwordx4 v[222:223], off
	s_waitcnt vmcnt(8)
	s_waitcnt lgkmcnt(0)
	s_barrier
	s_setprio 1
	s_waitcnt lgkmcnt(0)
	v_mfma_f32_16x16x32_bf16 v[62:65], v[130:133], v[162:165], v[62:65]
	v_mfma_f32_16x16x32_bf16 v[58:61], v[138:141], v[162:165], v[58:61]
	v_mfma_f32_16x16x32_bf16 v[54:57], v[130:133], v[170:173], v[54:57]
	v_mfma_f32_16x16x32_bf16 v[46:49], v[138:141], v[170:173], v[46:49]
	v_mfma_f32_16x16x32_bf16 v[38:41], v[130:133], v[178:181], v[38:41]
	v_mfma_f32_16x16x32_bf16 v[30:33], v[138:141], v[178:181], v[30:33]
	v_mfma_f32_16x16x32_bf16 v[22:25], v[130:133], v[208:211], v[22:25]
	v_mfma_f32_16x16x32_bf16 v[14:17], v[138:141], v[208:211], v[14:17]
	v_mfma_f32_16x16x32_bf16 v[62:65], v[134:137], v[166:169], v[62:65]
	v_mfma_f32_16x16x32_bf16 v[58:61], v[142:145], v[166:169], v[58:61]
	v_mfma_f32_16x16x32_bf16 v[54:57], v[134:137], v[174:177], v[54:57]
	v_mfma_f32_16x16x32_bf16 v[46:49], v[142:145], v[174:177], v[46:49]
	v_mfma_f32_16x16x32_bf16 v[38:41], v[134:137], v[204:207], v[38:41]
	v_mfma_f32_16x16x32_bf16 v[30:33], v[142:145], v[204:207], v[30:33]
	v_mfma_f32_16x16x32_bf16 v[22:25], v[134:137], v[212:215], v[22:25]
	v_mfma_f32_16x16x32_bf16 v[14:17], v[142:145], v[212:215], v[14:17]
	s_setprio 0
	s_setprio 1
	v_mfma_f32_16x16x32_bf16 v[50:53], v[146:149], v[162:165], v[50:53]
	v_mfma_f32_16x16x32_bf16 v[42:45], v[154:157], v[162:165], v[42:45]
	v_mfma_f32_16x16x32_bf16 v[34:37], v[146:149], v[170:173], v[34:37]
	v_mfma_f32_16x16x32_bf16 v[26:29], v[154:157], v[170:173], v[26:29]
	v_mfma_f32_16x16x32_bf16 v[18:21], v[146:149], v[178:181], v[18:21]
	v_mfma_f32_16x16x32_bf16 v[10:13], v[154:157], v[178:181], v[10:13]
	v_mfma_f32_16x16x32_bf16 v[6:9], v[146:149], v[208:211], v[6:9]
	v_mfma_f32_16x16x32_bf16 v[2:5], v[154:157], v[208:211], v[2:5]
	v_mfma_f32_16x16x32_bf16 v[50:53], v[150:153], v[166:169], v[50:53]
	v_mfma_f32_16x16x32_bf16 v[42:45], v[158:161], v[166:169], v[42:45]
	v_mfma_f32_16x16x32_bf16 v[34:37], v[150:153], v[174:177], v[34:37]
	v_mfma_f32_16x16x32_bf16 v[26:29], v[158:161], v[174:177], v[26:29]
	v_mfma_f32_16x16x32_bf16 v[18:21], v[150:153], v[204:207], v[18:21]
	v_mfma_f32_16x16x32_bf16 v[10:13], v[158:161], v[204:207], v[10:13]
	v_mfma_f32_16x16x32_bf16 v[6:9], v[150:153], v[212:215], v[6:9]
	v_mfma_f32_16x16x32_bf16 v[2:5], v[158:161], v[212:215], v[2:5]
	s_setprio 0
	s_barrier
	s_add_i32 s54, 0, 0x18000
	s_add_i32 s55, 0, 0x1c000
	v_add_u32_e32 v142, s54, v199
	v_add_u32_e32 v158, s55, v199
	ds_read_b128 v[130:133], v142
	ds_read_b128 v[134:137], v142 offset:1024
	ds_read_b128 v[138:141], v142 offset:2048
	ds_read_b128 v[142:145], v142 offset:3072
	ds_read_b128 v[146:149], v158
	ds_read_b128 v[150:153], v158 offset:1024
	ds_read_b128 v[154:157], v158 offset:2048
	ds_read_b128 v[158:161], v158 offset:3072
	s_add_u32 s28, s28, 0x80000
	s_addc_u32 s29, s29, 0
	s_mov_b32 m0, s37
	v_lshl_add_u64 v[224:225], s[28:29], 0, v[188:189]
	ds_read_b128 v[162:165], v202 offset:32768
	ds_read_b128 v[166:169], v202 offset:33792
	ds_read_b128 v[170:173], v202 offset:34816
	ds_read_b128 v[174:177], v202 offset:35840
	ds_read_b128 v[178:181], v202 offset:36864
	ds_read_b128 v[204:207], v202 offset:37888
	ds_read_b128 v[208:211], v202 offset:38912
	ds_read_b128 v[212:215], v202 offset:39936
	global_load_lds_dwordx4 v[224:225], off
	v_lshl_add_u64 v[224:225], s[28:29], 0, v[184:185]
	s_mov_b32 m0, s38
	s_nop 0
	global_load_lds_dwordx4 v[224:225], off
	s_waitcnt vmcnt(8)
	s_waitcnt lgkmcnt(0)
	s_barrier
	s_setprio 1
	s_waitcnt lgkmcnt(0)
	v_mfma_f32_16x16x32_bf16 v[126:129], v[130:133], v[162:165], v[126:129]
	v_mfma_f32_16x16x32_bf16 v[122:125], v[138:141], v[162:165], v[122:125]
	v_mfma_f32_16x16x32_bf16 v[118:121], v[130:133], v[170:173], v[118:121]
	v_mfma_f32_16x16x32_bf16 v[110:113], v[138:141], v[170:173], v[110:113]
	v_mfma_f32_16x16x32_bf16 v[102:105], v[130:133], v[178:181], v[102:105]
	v_mfma_f32_16x16x32_bf16 v[94:97], v[138:141], v[178:181], v[94:97]
	v_mfma_f32_16x16x32_bf16 v[86:89], v[130:133], v[208:211], v[86:89]
	v_mfma_f32_16x16x32_bf16 v[78:81], v[138:141], v[208:211], v[78:81]
	v_mfma_f32_16x16x32_bf16 v[126:129], v[134:137], v[166:169], v[126:129]
	v_mfma_f32_16x16x32_bf16 v[122:125], v[142:145], v[166:169], v[122:125]
	v_mfma_f32_16x16x32_bf16 v[118:121], v[134:137], v[174:177], v[118:121]
	v_mfma_f32_16x16x32_bf16 v[110:113], v[142:145], v[174:177], v[110:113]
	v_mfma_f32_16x16x32_bf16 v[102:105], v[134:137], v[204:207], v[102:105]
	v_mfma_f32_16x16x32_bf16 v[94:97], v[142:145], v[204:207], v[94:97]
	v_mfma_f32_16x16x32_bf16 v[86:89], v[134:137], v[212:215], v[86:89]
	v_mfma_f32_16x16x32_bf16 v[78:81], v[142:145], v[212:215], v[78:81]
	s_setprio 0
	s_setprio 1
	v_mfma_f32_16x16x32_bf16 v[114:117], v[146:149], v[162:165], v[114:117]
	v_mfma_f32_16x16x32_bf16 v[106:109], v[154:157], v[162:165], v[106:109]
	v_mfma_f32_16x16x32_bf16 v[98:101], v[146:149], v[170:173], v[98:101]
	v_mfma_f32_16x16x32_bf16 v[90:93], v[154:157], v[170:173], v[90:93]
	v_mfma_f32_16x16x32_bf16 v[82:85], v[146:149], v[178:181], v[82:85]
	v_mfma_f32_16x16x32_bf16 v[74:77], v[154:157], v[178:181], v[74:77]
	v_mfma_f32_16x16x32_bf16 v[70:73], v[146:149], v[208:211], v[70:73]
	v_mfma_f32_16x16x32_bf16 v[66:69], v[154:157], v[208:211], v[66:69]
	v_mfma_f32_16x16x32_bf16 v[114:117], v[150:153], v[166:169], v[114:117]
	v_mfma_f32_16x16x32_bf16 v[106:109], v[158:161], v[166:169], v[106:109]
	v_mfma_f32_16x16x32_bf16 v[98:101], v[150:153], v[174:177], v[98:101]
	v_mfma_f32_16x16x32_bf16 v[90:93], v[158:161], v[174:177], v[90:93]
	v_mfma_f32_16x16x32_bf16 v[82:85], v[150:153], v[204:207], v[82:85]
	v_mfma_f32_16x16x32_bf16 v[74:77], v[158:161], v[204:207], v[74:77]
	v_mfma_f32_16x16x32_bf16 v[70:73], v[150:153], v[212:215], v[70:73]
	v_mfma_f32_16x16x32_bf16 v[66:69], v[158:161], v[212:215], v[66:69]
	s_setprio 0
	s_barrier
	s_add_i32 s28, s54, s31
	v_lshl_add_u64 v[216:217], v[216:217], 0, s[12:13]
	s_mov_b32 m0, s28
	ds_read_b128 v[162:165], v202 offset:49152
	ds_read_b128 v[166:169], v202 offset:50176
	ds_read_b128 v[170:173], v202 offset:51200
	ds_read_b128 v[174:177], v202 offset:52224
	ds_read_b128 v[178:181], v202 offset:53248
	ds_read_b128 v[204:207], v202 offset:54272
	ds_read_b128 v[208:211], v202 offset:55296
	ds_read_b128 v[212:215], v202 offset:56320
	global_load_lds_dwordx4 v[216:217], off
	s_add_i32 m0, s28, 0x2000
	s_add_u32 s26, s26, 0x80080
	v_lshl_add_u64 v[216:217], v[218:219], 0, s[12:13]
	s_addc_u32 s27, s27, 0
	s_add_i32 s28, s55, s31
	global_load_lds_dwordx4 v[216:217], off
	v_lshl_add_u64 v[216:217], s[26:27], 0, v[186:187]
	s_mov_b32 m0, s28
	s_nop 0
	global_load_lds_dwordx4 v[216:217], off
	v_lshl_add_u64 v[216:217], s[26:27], 0, v[182:183]
	s_add_i32 m0, s28, 0x2000
	s_nop 0
	global_load_lds_dwordx4 v[216:217], off
	v_lshl_add_u64 v[216:217], v[220:221], 0, s[12:13]
	s_mov_b32 m0, s42
	s_nop 0
	global_load_lds_dwordx4 v[216:217], off
	v_lshl_add_u64 v[216:217], v[222:223], 0, s[12:13]
	s_mov_b32 m0, s43
	s_nop 0
	global_load_lds_dwordx4 v[216:217], off
	s_waitcnt vmcnt(8)
	s_waitcnt lgkmcnt(0)
	s_barrier
	s_setprio 1
	s_waitcnt lgkmcnt(0)
	v_mfma_f32_16x16x32_bf16 v[62:65], v[130:133], v[162:165], v[62:65]
	v_mfma_f32_16x16x32_bf16 v[58:61], v[138:141], v[162:165], v[58:61]
	v_mfma_f32_16x16x32_bf16 v[54:57], v[130:133], v[170:173], v[54:57]
	v_mfma_f32_16x16x32_bf16 v[46:49], v[138:141], v[170:173], v[46:49]
	v_mfma_f32_16x16x32_bf16 v[38:41], v[130:133], v[178:181], v[38:41]
	v_mfma_f32_16x16x32_bf16 v[30:33], v[138:141], v[178:181], v[30:33]
	v_mfma_f32_16x16x32_bf16 v[22:25], v[130:133], v[208:211], v[22:25]
	v_mfma_f32_16x16x32_bf16 v[14:17], v[138:141], v[208:211], v[14:17]
	v_mfma_f32_16x16x32_bf16 v[62:65], v[134:137], v[166:169], v[62:65]
	v_mfma_f32_16x16x32_bf16 v[58:61], v[142:145], v[166:169], v[58:61]
	v_mfma_f32_16x16x32_bf16 v[54:57], v[134:137], v[174:177], v[54:57]
	v_mfma_f32_16x16x32_bf16 v[46:49], v[142:145], v[174:177], v[46:49]
	v_mfma_f32_16x16x32_bf16 v[38:41], v[134:137], v[204:207], v[38:41]
	v_mfma_f32_16x16x32_bf16 v[30:33], v[142:145], v[204:207], v[30:33]
	v_mfma_f32_16x16x32_bf16 v[22:25], v[134:137], v[212:215], v[22:25]
	v_mfma_f32_16x16x32_bf16 v[14:17], v[142:145], v[212:215], v[14:17]
	s_setprio 0
	s_setprio 1
	v_mfma_f32_16x16x32_bf16 v[50:53], v[146:149], v[162:165], v[50:53]
	v_mfma_f32_16x16x32_bf16 v[42:45], v[154:157], v[162:165], v[42:45]
	v_mfma_f32_16x16x32_bf16 v[34:37], v[146:149], v[170:173], v[34:37]
	v_mfma_f32_16x16x32_bf16 v[26:29], v[154:157], v[170:173], v[26:29]
	v_mfma_f32_16x16x32_bf16 v[18:21], v[146:149], v[178:181], v[18:21]
	v_mfma_f32_16x16x32_bf16 v[10:13], v[154:157], v[178:181], v[10:13]
	v_mfma_f32_16x16x32_bf16 v[6:9], v[146:149], v[208:211], v[6:9]
	v_mfma_f32_16x16x32_bf16 v[2:5], v[154:157], v[208:211], v[2:5]
	v_mfma_f32_16x16x32_bf16 v[50:53], v[150:153], v[166:169], v[50:53]
	v_mfma_f32_16x16x32_bf16 v[42:45], v[158:161], v[166:169], v[42:45]
	v_mfma_f32_16x16x32_bf16 v[34:37], v[150:153], v[174:177], v[34:37]
	v_mfma_f32_16x16x32_bf16 v[26:29], v[158:161], v[174:177], v[26:29]
	v_mfma_f32_16x16x32_bf16 v[18:21], v[150:153], v[204:207], v[18:21]
	v_mfma_f32_16x16x32_bf16 v[10:13], v[158:161], v[204:207], v[10:13]
	v_mfma_f32_16x16x32_bf16 v[6:9], v[150:153], v[212:215], v[6:9]
	v_mfma_f32_16x16x32_bf16 v[2:5], v[158:161], v[212:215], v[2:5]
	s_setprio 0
	s_barrier
	s_add_i32 s53, s53, 2
	s_add_u32 s8, s8, 0x100
	s_addc_u32 s9, s9, 0
	s_add_u32 s51, s51, 0x100
	s_addc_u32 s52, s52, 0
	s_cmp_gt_u32 s53, 29
	s_cbranch_scc0 .LBB0_1942
	s_and_b64 vcc, exec, s[14:15]
	s_cbranch_vccz .LBB0_1945
	s_barrier

.LBB0_2739:
	s_or_b64 exec, exec, s[2:3]
	s_waitcnt lgkmcnt(0)
	s_barrier
	s_waitcnt vmcnt(0)
	ds_read_b32 v2, v245
	s_mov_b64 s[2:3], -1
	s_waitcnt lgkmcnt(0)
	v_readfirstlane_b32 s4, v2
	s_cmpk_gt_i32 s4, 0x7f
	s_cbranch_scc1 .LBB0_2734
	v_mov_b32_e32 v6, v0
	s_barrier
	s_lshr_b32 s3, s4, 6
	v_add_u32_e32 v2, 0xffffff00, v6
	v_sub_u32_e32 v4, 0, v2
	v_max_i32_e32 v4, v2, v4
	v_mul_lo_u32 v2, v2, v2
	s_and_b32 s4, s4, 63
	v_ffbh_u32_e32 v2, v2
	s_sub_i32 s2, 63, s4
	s_or_b32 s5, s3, s40
	s_mov_b32 s3, s45
	v_sub_u32_e32 v2, 33, v2
	s_lshl_b64 s[8:9], s[2:3], 7
	v_cmp_gt_u32_e32 vcc, 8, v4
	v_min_u32_e32 v2, 15, v2
	s_movk_i32 s3, 0x100
	v_cndmask_b32_e32 v2, v2, v4, vcc
	v_cmp_lt_i32_e32 vcc, s3, v6
	s_add_u32 s76, s8, s41
	s_addc_u32 s77, s9, 0
	v_cndmask_b32_e64 v4, 0, 16, vcc
	v_add_u32_e32 v2, v2, v4
	v_readlane_b32 s8, v254, 32
	v_lshl_or_b32 v2, v2, 3, s5
	v_readlane_b32 s9, v254, 33
	s_lshl_b32 s3, s5, 8
	s_or_b32 s5, s3, s85
	v_lshl_add_u64 v[4:5], v[2:3], 2, s[8:9]
	global_load_dword v2, v[4:5], off
	v_lshl_add_u32 v4, v6, 2, 0
	v_add_u32_e32 v4, 0x20000, v4
	v_mov_b32_e32 v6, v242
	v_readlane_b32 s8, v254, 3
	v_readlane_b32 s9, v254, 4
	s_lshl_b32 s44, s5, 1
	s_andn2_b64 vcc, exec, s[56:57]
	v_readlane_b32 s10, v254, 34
	v_readlane_b32 s11, v254, 35
	v_readlane_b32 s12, v254, 36
	v_readlane_b32 s13, v254, 37
	v_readlane_b32 s14, v254, 38
	v_readlane_b32 s15, v254, 39
	v_readlane_b32 s16, v254, 40
	v_readlane_b32 s17, v254, 41
	v_readlane_b32 s18, v254, 42
	v_readlane_b32 s19, v254, 43
	v_readlane_b32 s20, v254, 44
	v_readlane_b32 s21, v254, 45
	v_readlane_b32 s22, v254, 46
	v_readlane_b32 s23, v254, 47
	s_waitcnt vmcnt(0)
	v_mul_f32_e32 v2, 0x3fb8aa3b, v2
	ds_write_b32 v4, v2
	s_nop 0
	v_and_or_b32 v2, v6, 31, s46
	v_lshl_add_u64 v[4:5], s[76:77], 0, v[2:3]
	v_lshlrev_b64 v[4:5], 12, v[4:5]
	v_ashrrev_i32_e32 v2, 2, v6
	v_lshl_add_u64 v[4:5], s[8:9], 0, v[4:5]
	v_and_b32_e32 v6, -8, v2
	v_lshl_add_u64 v[4:5], v[4:5], 0, s[44:45]
	v_ashrrev_i32_e32 v7, 31, v6
	v_lshl_add_u64 v[4:5], v[6:7], 1, v[4:5]
	v_cmp_ne_u32_e64 s[8:9], 1, v243
	s_cbranch_vccnz .LBB0_2749
	global_load_dwordx4 v[210:213], v[4:5], off
	s_and_b64 vcc, exec, s[8:9]
	s_cbranch_vccz .LBB0_2750

.LBB0_3201:
	ds_read_b128 v[146:149], v164
	ds_read_b128 v[150:153], v164 offset:1024
	ds_read_b128 v[154:157], v164 offset:2048
	ds_read_b128 v[158:161], v164 offset:3072
	ds_read_b128 v[168:171], v165
	ds_read_b128 v[172:175], v165 offset:1024
	ds_read_b128 v[176:179], v165 offset:2048
	ds_read_b128 v[180:183], v165 offset:3072
	s_add_u32 s40, s8, 0xfff80080
	s_addc_u32 s41, s9, -1
	s_cmp_eq_u32 s66, 28
	s_cselect_b32 s43, s7, s41
	s_cselect_b32 s42, s35, s40
	s_cselect_b32 s41, s31, s65
	s_cselect_b32 s40, s63, s64
	v_lshl_add_u64 v[216:217], s[8:9], 0, v[138:139]
	s_add_i32 m0, s46, 0xc000
	ds_read_b128 v[184:187], v166
	ds_read_b128 v[188:191], v166 offset:1024
	ds_read_b128 v[192:195], v166 offset:2048
	ds_read_b128 v[196:199], v166 offset:3072
	ds_read_b128 v[200:203], v166 offset:4096
	ds_read_b128 v[204:207], v166 offset:5120
	ds_read_b128 v[208:211], v166 offset:6144
	ds_read_b128 v[212:215], v166 offset:7168
	global_load_lds_dwordx4 v[216:217], off
	v_lshl_add_u64 v[216:217], s[8:9], 0, v[140:141]
	s_add_i32 m0, s46, 0xe000
	s_nop 0
	global_load_lds_dwordx4 v[216:217], off
	s_waitcnt vmcnt(8)
	s_waitcnt lgkmcnt(0)
	s_barrier
	s_setprio 1
	s_waitcnt lgkmcnt(0)
	v_mfma_f32_16x16x32_bf16 v[126:129], v[146:149], v[184:187], v[126:129]
	v_mfma_f32_16x16x32_bf16 v[122:125], v[154:157], v[184:187], v[122:125]
	v_mfma_f32_16x16x32_bf16 v[118:121], v[146:149], v[192:195], v[118:121]
	v_mfma_f32_16x16x32_bf16 v[110:113], v[154:157], v[192:195], v[110:113]
	v_mfma_f32_16x16x32_bf16 v[102:105], v[146:149], v[200:203], v[102:105]
	v_mfma_f32_16x16x32_bf16 v[94:97], v[154:157], v[200:203], v[94:97]
	v_mfma_f32_16x16x32_bf16 v[86:89], v[146:149], v[208:211], v[86:89]
	v_mfma_f32_16x16x32_bf16 v[78:81], v[154:157], v[208:211], v[78:81]
	v_mfma_f32_16x16x32_bf16 v[126:129], v[150:153], v[188:191], v[126:129]
	v_mfma_f32_16x16x32_bf16 v[122:125], v[158:161], v[188:191], v[122:125]
	v_mfma_f32_16x16x32_bf16 v[118:121], v[150:153], v[196:199], v[118:121]
	v_mfma_f32_16x16x32_bf16 v[110:113], v[158:161], v[196:199], v[110:113]
	v_mfma_f32_16x16x32_bf16 v[102:105], v[150:153], v[204:207], v[102:105]
	v_mfma_f32_16x16x32_bf16 v[94:97], v[158:161], v[204:207], v[94:97]
	v_mfma_f32_16x16x32_bf16 v[86:89], v[150:153], v[212:215], v[86:89]
	v_mfma_f32_16x16x32_bf16 v[78:81], v[158:161], v[212:215], v[78:81]
	s_setprio 0
	s_setprio 1
	v_mfma_f32_16x16x32_bf16 v[114:117], v[168:171], v[184:187], v[114:117]
	v_mfma_f32_16x16x32_bf16 v[106:109], v[176:179], v[184:187], v[106:109]
	v_mfma_f32_16x16x32_bf16 v[98:101], v[168:171], v[192:195], v[98:101]
	v_mfma_f32_16x16x32_bf16 v[90:93], v[176:179], v[192:195], v[90:93]
	v_mfma_f32_16x16x32_bf16 v[82:85], v[168:171], v[200:203], v[82:85]
	v_mfma_f32_16x16x32_bf16 v[74:77], v[176:179], v[200:203], v[74:77]
	v_mfma_f32_16x16x32_bf16 v[70:73], v[168:171], v[208:211], v[70:73]
	v_mfma_f32_16x16x32_bf16 v[66:69], v[176:179], v[208:211], v[66:69]
	v_mfma_f32_16x16x32_bf16 v[114:117], v[172:175], v[188:191], v[114:117]
	v_mfma_f32_16x16x32_bf16 v[106:109], v[180:183], v[188:191], v[106:109]
	v_mfma_f32_16x16x32_bf16 v[98:101], v[172:175], v[196:199], v[98:101]
	v_mfma_f32_16x16x32_bf16 v[90:93], v[180:183], v[196:199], v[90:93]
	v_mfma_f32_16x16x32_bf16 v[82:85], v[172:175], v[204:207], v[82:85]
	v_mfma_f32_16x16x32_bf16 v[74:77], v[180:183], v[204:207], v[74:77]
	v_mfma_f32_16x16x32_bf16 v[70:73], v[172:175], v[212:215], v[70:73]
	v_mfma_f32_16x16x32_bf16 v[66:69], v[180:183], v[212:215], v[66:69]
	s_setprio 0
	s_barrier
	s_add_i32 s67, s56, s33
	v_lshl_add_u64 v[216:217], s[40:41], 0, v[134:135]
	s_mov_b32 m0, s67
	ds_read_b128 v[184:187], v166 offset:16384
	ds_read_b128 v[188:191], v166 offset:17408
	ds_read_b128 v[192:195], v166 offset:18432
	ds_read_b128 v[196:199], v166 offset:19456
	ds_read_b128 v[200:203], v166 offset:20480
	ds_read_b128 v[204:207], v166 offset:21504
	ds_read_b128 v[208:211], v166 offset:22528
	ds_read_b128 v[212:215], v166 offset:23552
	global_load_lds_dwordx4 v[216:217], off
	s_add_i32 m0, s67, 0x2000
	s_add_u32 s68, s40, 0x80000
	v_lshl_add_u64 v[218:219], s[40:41], 0, v[130:131]
	s_addc_u32 s69, s41, 0
	s_add_i32 s67, s57, s33
	global_load_lds_dwordx4 v[218:219], off
	v_lshl_add_u64 v[220:221], s[68:69], 0, v[134:135]
	s_mov_b32 m0, s67
	v_lshl_add_u64 v[222:223], s[42:43], 0, v[132:133]
	global_load_lds_dwordx4 v[220:221], off
	v_lshl_add_u64 v[220:221], s[68:69], 0, v[130:131]
	s_add_i32 m0, s67, 0x2000
	s_nop 0
	global_load_lds_dwordx4 v[220:221], off
	v_lshl_add_u64 v[220:221], s[42:43], 0, v[136:137]
	s_mov_b32 m0, s46
	s_nop 0
	global_load_lds_dwordx4 v[220:221], off
	s_mov_b32 m0, s47
	s_nop 0
	global_load_lds_dwordx4 v[222:223], off
	s_waitcnt vmcnt(8)
	s_waitcnt lgkmcnt(0)
	s_barrier
	s_setprio 1
	s_waitcnt lgkmcnt(0)
	v_mfma_f32_16x16x32_bf16 v[62:65], v[146:149], v[184:187], v[62:65]
	v_mfma_f32_16x16x32_bf16 v[58:61], v[154:157], v[184:187], v[58:61]
	v_mfma_f32_16x16x32_bf16 v[54:57], v[146:149], v[192:195], v[54:57]
	v_mfma_f32_16x16x32_bf16 v[46:49], v[154:157], v[192:195], v[46:49]
	v_mfma_f32_16x16x32_bf16 v[38:41], v[146:149], v[200:203], v[38:41]
	v_mfma_f32_16x16x32_bf16 v[30:33], v[154:157], v[200:203], v[30:33]
	v_mfma_f32_16x16x32_bf16 v[22:25], v[146:149], v[208:211], v[22:25]
	v_mfma_f32_16x16x32_bf16 v[14:17], v[154:157], v[208:211], v[14:17]
	v_mfma_f32_16x16x32_bf16 v[62:65], v[150:153], v[188:191], v[62:65]
	v_mfma_f32_16x16x32_bf16 v[58:61], v[158:161], v[188:191], v[58:61]
	v_mfma_f32_16x16x32_bf16 v[54:57], v[150:153], v[196:199], v[54:57]
	v_mfma_f32_16x16x32_bf16 v[46:49], v[158:161], v[196:199], v[46:49]
	v_mfma_f32_16x16x32_bf16 v[38:41], v[150:153], v[204:207], v[38:41]
	v_mfma_f32_16x16x32_bf16 v[30:33], v[158:161], v[204:207], v[30:33]
	v_mfma_f32_16x16x32_bf16 v[22:25], v[150:153], v[212:215], v[22:25]
	v_mfma_f32_16x16x32_bf16 v[14:17], v[158:161], v[212:215], v[14:17]
	s_setprio 0
	s_setprio 1
	v_mfma_f32_16x16x32_bf16 v[50:53], v[168:171], v[184:187], v[50:53]
	v_mfma_f32_16x16x32_bf16 v[42:45], v[176:179], v[184:187], v[42:45]
	v_mfma_f32_16x16x32_bf16 v[34:37], v[168:171], v[192:195], v[34:37]
	v_mfma_f32_16x16x32_bf16 v[26:29], v[176:179], v[192:195], v[26:29]
	v_mfma_f32_16x16x32_bf16 v[18:21], v[168:171], v[200:203], v[18:21]
	v_mfma_f32_16x16x32_bf16 v[10:13], v[176:179], v[200:203], v[10:13]
	v_mfma_f32_16x16x32_bf16 v[6:9], v[168:171], v[208:211], v[6:9]
	v_mfma_f32_16x16x32_bf16 v[2:5], v[176:179], v[208:211], v[2:5]
	v_mfma_f32_16x16x32_bf16 v[50:53], v[172:175], v[188:191], v[50:53]
	v_mfma_f32_16x16x32_bf16 v[42:45], v[180:183], v[188:191], v[42:45]
	v_mfma_f32_16x16x32_bf16 v[34:37], v[172:175], v[196:199], v[34:37]
	v_mfma_f32_16x16x32_bf16 v[26:29], v[180:183], v[196:199], v[26:29]
	v_mfma_f32_16x16x32_bf16 v[18:21], v[172:175], v[204:207], v[18:21]
	v_mfma_f32_16x16x32_bf16 v[10:13], v[180:183], v[204:207], v[10:13]
	v_mfma_f32_16x16x32_bf16 v[6:9], v[172:175], v[212:215], v[6:9]
	v_mfma_f32_16x16x32_bf16 v[2:5], v[180:183], v[212:215], v[2:5]
	s_setprio 0
	s_barrier
	s_add_i32 s67, 0, 0x18000
	s_add_i32 s68, 0, 0x1c000
	v_add_u32_e32 v158, s67, v163
	v_add_u32_e32 v180, s68, v163
	ds_read_b128 v[146:149], v158
	ds_read_b128 v[150:153], v158 offset:1024
	ds_read_b128 v[154:157], v158 offset:2048
	ds_read_b128 v[158:161], v158 offset:3072
	ds_read_b128 v[168:171], v180
	ds_read_b128 v[172:175], v180 offset:1024
	ds_read_b128 v[176:179], v180 offset:2048
	ds_read_b128 v[180:183], v180 offset:3072
	s_add_u32 s42, s42, 0x80000
	s_addc_u32 s43, s43, 0
	s_mov_b32 m0, s48
	v_lshl_add_u64 v[224:225], s[42:43], 0, v[136:137]
	ds_read_b128 v[184:187], v166 offset:32768
	ds_read_b128 v[188:191], v166 offset:33792
	ds_read_b128 v[192:195], v166 offset:34816
	ds_read_b128 v[196:199], v166 offset:35840
	ds_read_b128 v[200:203], v166 offset:36864
	ds_read_b128 v[204:207], v166 offset:37888
	ds_read_b128 v[208:211], v166 offset:38912
	ds_read_b128 v[212:215], v166 offset:39936
	global_load_lds_dwordx4 v[224:225], off
	v_lshl_add_u64 v[224:225], s[42:43], 0, v[132:133]
	s_mov_b32 m0, s49
	s_nop 0
	global_load_lds_dwordx4 v[224:225], off
	s_waitcnt vmcnt(8)
	s_waitcnt lgkmcnt(0)
	s_barrier
	s_setprio 1
	s_waitcnt lgkmcnt(0)
	v_mfma_f32_16x16x32_bf16 v[126:129], v[146:149], v[184:187], v[126:129]
	v_mfma_f32_16x16x32_bf16 v[122:125], v[154:157], v[184:187], v[122:125]
	v_mfma_f32_16x16x32_bf16 v[118:121], v[146:149], v[192:195], v[118:121]
	v_mfma_f32_16x16x32_bf16 v[110:113], v[154:157], v[192:195], v[110:113]
	v_mfma_f32_16x16x32_bf16 v[102:105], v[146:149], v[200:203], v[102:105]
	v_mfma_f32_16x16x32_bf16 v[94:97], v[154:157], v[200:203], v[94:97]
	v_mfma_f32_16x16x32_bf16 v[86:89], v[146:149], v[208:211], v[86:89]
	v_mfma_f32_16x16x32_bf16 v[78:81], v[154:157], v[208:211], v[78:81]
	v_mfma_f32_16x16x32_bf16 v[126:129], v[150:153], v[188:191], v[126:129]
	v_mfma_f32_16x16x32_bf16 v[122:125], v[158:161], v[188:191], v[122:125]
	v_mfma_f32_16x16x32_bf16 v[118:121], v[150:153], v[196:199], v[118:121]
	v_mfma_f32_16x16x32_bf16 v[110:113], v[158:161], v[196:199], v[110:113]
	v_mfma_f32_16x16x32_bf16 v[102:105], v[150:153], v[204:207], v[102:105]
	v_mfma_f32_16x16x32_bf16 v[94:97], v[158:161], v[204:207], v[94:97]
	v_mfma_f32_16x16x32_bf16 v[86:89], v[150:153], v[212:215], v[86:89]
	v_mfma_f32_16x16x32_bf16 v[78:81], v[158:161], v[212:215], v[78:81]
	s_setprio 0
	s_setprio 1
	v_mfma_f32_16x16x32_bf16 v[114:117], v[168:171], v[184:187], v[114:117]
	v_mfma_f32_16x16x32_bf16 v[106:109], v[176:179], v[184:187], v[106:109]
	v_mfma_f32_16x16x32_bf16 v[98:101], v[168:171], v[192:195], v[98:101]
	v_mfma_f32_16x16x32_bf16 v[90:93], v[176:179], v[192:195], v[90:93]
	v_mfma_f32_16x16x32_bf16 v[82:85], v[168:171], v[200:203], v[82:85]
	v_mfma_f32_16x16x32_bf16 v[74:77], v[176:179], v[200:203], v[74:77]
	v_mfma_f32_16x16x32_bf16 v[70:73], v[168:171], v[208:211], v[70:73]
	v_mfma_f32_16x16x32_bf16 v[66:69], v[176:179], v[208:211], v[66:69]
	v_mfma_f32_16x16x32_bf16 v[114:117], v[172:175], v[188:191], v[114:117]
	v_mfma_f32_16x16x32_bf16 v[106:109], v[180:183], v[188:191], v[106:109]
	v_mfma_f32_16x16x32_bf16 v[98:101], v[172:175], v[196:199], v[98:101]
	v_mfma_f32_16x16x32_bf16 v[90:93], v[180:183], v[196:199], v[90:93]
	v_mfma_f32_16x16x32_bf16 v[82:85], v[172:175], v[204:207], v[82:85]
	v_mfma_f32_16x16x32_bf16 v[74:77], v[180:183], v[204:207], v[74:77]
	v_mfma_f32_16x16x32_bf16 v[70:73], v[172:175], v[212:215], v[70:73]
	v_mfma_f32_16x16x32_bf16 v[66:69], v[180:183], v[212:215], v[66:69]
	s_setprio 0
	s_barrier
	s_add_i32 s42, s67, s33
	v_lshl_add_u64 v[216:217], v[216:217], 0, s[12:13]
	s_mov_b32 m0, s42
	ds_read_b128 v[184:187], v166 offset:49152
	ds_read_b128 v[188:191], v166 offset:50176
	ds_read_b128 v[192:195], v166 offset:51200
	ds_read_b128 v[196:199], v166 offset:52224
	ds_read_b128 v[200:203], v166 offset:53248
	ds_read_b128 v[204:207], v166 offset:54272
	ds_read_b128 v[208:211], v166 offset:55296
	ds_read_b128 v[212:215], v166 offset:56320
	global_load_lds_dwordx4 v[216:217], off
	s_add_i32 m0, s42, 0x2000
	s_add_u32 s40, s40, 0x80080
	v_lshl_add_u64 v[216:217], v[218:219], 0, s[12:13]
	s_addc_u32 s41, s41, 0
	s_add_i32 s42, s68, s33
	global_load_lds_dwordx4 v[216:217], off
	v_lshl_add_u64 v[216:217], s[40:41], 0, v[134:135]
	s_mov_b32 m0, s42
	s_nop 0
	global_load_lds_dwordx4 v[216:217], off
	v_lshl_add_u64 v[216:217], s[40:41], 0, v[130:131]
	s_add_i32 m0, s42, 0x2000
	s_nop 0
	global_load_lds_dwordx4 v[216:217], off
	v_lshl_add_u64 v[216:217], v[220:221], 0, s[12:13]
	s_mov_b32 m0, s53
	s_nop 0
	global_load_lds_dwordx4 v[216:217], off
	v_lshl_add_u64 v[216:217], v[222:223], 0, s[12:13]
	s_mov_b32 m0, s54
	s_nop 0
	global_load_lds_dwordx4 v[216:217], off
	s_waitcnt vmcnt(8)
	s_waitcnt lgkmcnt(0)
	s_barrier
	s_setprio 1
	s_waitcnt lgkmcnt(0)
	v_mfma_f32_16x16x32_bf16 v[62:65], v[146:149], v[184:187], v[62:65]
	v_mfma_f32_16x16x32_bf16 v[58:61], v[154:157], v[184:187], v[58:61]
	v_mfma_f32_16x16x32_bf16 v[54:57], v[146:149], v[192:195], v[54:57]
	v_mfma_f32_16x16x32_bf16 v[46:49], v[154:157], v[192:195], v[46:49]
	v_mfma_f32_16x16x32_bf16 v[38:41], v[146:149], v[200:203], v[38:41]
	v_mfma_f32_16x16x32_bf16 v[30:33], v[154:157], v[200:203], v[30:33]
	v_mfma_f32_16x16x32_bf16 v[22:25], v[146:149], v[208:211], v[22:25]
	v_mfma_f32_16x16x32_bf16 v[14:17], v[154:157], v[208:211], v[14:17]
	v_mfma_f32_16x16x32_bf16 v[62:65], v[150:153], v[188:191], v[62:65]
	v_mfma_f32_16x16x32_bf16 v[58:61], v[158:161], v[188:191], v[58:61]
	v_mfma_f32_16x16x32_bf16 v[54:57], v[150:153], v[196:199], v[54:57]
	v_mfma_f32_16x16x32_bf16 v[46:49], v[158:161], v[196:199], v[46:49]
	v_mfma_f32_16x16x32_bf16 v[38:41], v[150:153], v[204:207], v[38:41]
	v_mfma_f32_16x16x32_bf16 v[30:33], v[158:161], v[204:207], v[30:33]
	v_mfma_f32_16x16x32_bf16 v[22:25], v[150:153], v[212:215], v[22:25]
	v_mfma_f32_16x16x32_bf16 v[14:17], v[158:161], v[212:215], v[14:17]
	s_setprio 0
	s_setprio 1
	v_mfma_f32_16x16x32_bf16 v[50:53], v[168:171], v[184:187], v[50:53]
	v_mfma_f32_16x16x32_bf16 v[42:45], v[176:179], v[184:187], v[42:45]
	v_mfma_f32_16x16x32_bf16 v[34:37], v[168:171], v[192:195], v[34:37]
	v_mfma_f32_16x16x32_bf16 v[26:29], v[176:179], v[192:195], v[26:29]
	v_mfma_f32_16x16x32_bf16 v[18:21], v[168:171], v[200:203], v[18:21]
	v_mfma_f32_16x16x32_bf16 v[10:13], v[176:179], v[200:203], v[10:13]
	v_mfma_f32_16x16x32_bf16 v[6:9], v[168:171], v[208:211], v[6:9]
	v_mfma_f32_16x16x32_bf16 v[2:5], v[176:179], v[208:211], v[2:5]
	v_mfma_f32_16x16x32_bf16 v[50:53], v[172:175], v[188:191], v[50:53]
	v_mfma_f32_16x16x32_bf16 v[42:45], v[180:183], v[188:191], v[42:45]
	v_mfma_f32_16x16x32_bf16 v[34:37], v[172:175], v[196:199], v[34:37]
	v_mfma_f32_16x16x32_bf16 v[26:29], v[180:183], v[196:199], v[26:29]
	v_mfma_f32_16x16x32_bf16 v[18:21], v[172:175], v[204:207], v[18:21]
	v_mfma_f32_16x16x32_bf16 v[10:13], v[180:183], v[204:207], v[10:13]
	v_mfma_f32_16x16x32_bf16 v[6:9], v[172:175], v[212:215], v[6:9]
	v_mfma_f32_16x16x32_bf16 v[2:5], v[180:183], v[212:215], v[2:5]
	s_setprio 0
	s_barrier
	s_add_i32 s66, s66, 2
	s_add_u32 s8, s8, 0x100
	s_addc_u32 s9, s9, 0
	s_add_u32 s64, s64, 0x100
	s_addc_u32 s65, s65, 0
	s_cmp_gt_u32 s66, 29
	s_cbranch_scc0 .LBB0_3201
	s_and_b64 vcc, exec, s[14:15]
	s_cbranch_vccz .LBB0_3204
	s_barrier
